# phase 1 bias GEMV: partial sums of a workgroup's 8 waves reduced in LDS, one atomic per address per workgroup (8 adds per address instead of 64)
# speedup vs baseline: 1.0021x; 1.0021x over previous
.Lp1_noctx0:
	global_load_dwordx4 v[20:23], v0, s[52:53]
	global_load_dwordx4 v[24:27], v0, s[52:53] offset:1024
	global_load_dwordx4 v[28:31], v0, s[52:53] offset:2048
	global_load_dwordx4 v[32:35], v0, s[52:53] offset:3072
	s_add_u32 s14, s12, 0x0
	s_addc_u32 s15, s13, 0
	s_add_u32 s16, s14, 0x1000
	s_addc_u32 s17, s15, 0
	global_load_dwordx4 v[36:39], v0, s[14:15]
	global_load_dwordx4 v[40:43], v0, s[14:15] offset:1024
	global_load_dwordx4 v[44:47], v0, s[14:15] offset:2048
	global_load_dwordx4 v[48:51], v0, s[14:15] offset:3072
	global_load_dwordx4 v[52:55], v0, s[16:17]
	global_load_dwordx4 v[56:59], v0, s[16:17] offset:1024
	global_load_dwordx4 v[60:63], v0, s[16:17] offset:2048
	global_load_dwordx4 v[64:67], v0, s[16:17] offset:3072
	s_mov_b32 s16, s33
	s_cmpk_lt_u32 s16, 0xb0
	s_cbranch_scc0 .Lp1_nob0
	s_mul_i32 s17, s16, 0xba3
	s_lshr_b32 s17, s17, 16
	s_mul_i32 s18, s17, 22
	s_sub_i32 s18, s16, s18
	s_lshl_b32 s17, s17, 3
	s_add_i32 s17, s17, s7
	s_mul_i32 s19, s17, 0x58000
	s_add_u32 s22, s84, s19
	s_addc_u32 s23, s85, 0
	v_and_b32_e32 v3, 31, v2
	v_lshrrev_b32_e32 v8, 5, v2
	v_lshlrev_b32_e32 v3, 4, v3
	s_lshl_b32 s19, s18, 9
	v_mul_u32_u24_e32 v8, 0x2c00, v8
	v_add_u32_e32 v190, v8, v3
	v_add_u32_e32 v190, s19, v190
	global_load_dwordx4 v[148:151], v190, s[22:23]
	s_add_u32 s22, s22, 0x5800
	s_addc_u32 s23, s23, 0
	global_load_dwordx4 v[152:155], v190, s[22:23]
	s_add_u32 s22, s22, 0x5800
	s_addc_u32 s23, s23, 0
	global_load_dwordx4 v[156:159], v190, s[22:23]
	s_add_u32 s22, s22, 0x5800
	s_addc_u32 s23, s23, 0
	global_load_dwordx4 v[160:163], v190, s[22:23]
	s_add_u32 s22, s22, 0x5800
	s_addc_u32 s23, s23, 0
	global_load_dwordx4 v[164:167], v190, s[22:23]
	s_add_u32 s22, s22, 0x5800
	s_addc_u32 s23, s23, 0
	global_load_dwordx4 v[168:171], v190, s[22:23]
	s_add_u32 s22, s22, 0x5800
	s_addc_u32 s23, s23, 0
	global_load_dwordx4 v[172:175], v190, s[22:23]
	s_add_u32 s22, s22, 0x5800
	s_addc_u32 s23, s23, 0
	global_load_dwordx4 v[176:179], v190, s[22:23]
	s_add_u32 s22, s22, 0x5800
	s_addc_u32 s23, s23, 0
	global_load_dwordx4 v[180:183], v190, s[22:23]
	s_add_u32 s22, s22, 0x5800
	s_addc_u32 s23, s23, 0
	global_load_dwordx4 v[184:187], v190, s[22:23]
	s_add_u32 s22, s22, 0x5800
	s_addc_u32 s23, s23, 0
	global_load_dwordx4 v[192:195], v190, s[22:23]
	s_add_u32 s22, s22, 0x5800
	s_addc_u32 s23, s23, 0
	global_load_dwordx4 v[196:199], v190, s[22:23]
	s_add_u32 s22, s22, 0x5800
	s_addc_u32 s23, s23, 0
	global_load_dwordx4 v[200:203], v190, s[22:23]
	s_add_u32 s22, s22, 0x5800
	s_addc_u32 s23, s23, 0
	global_load_dwordx4 v[204:207], v190, s[22:23]
	s_add_u32 s22, s22, 0x5800
	s_addc_u32 s23, s23, 0
	global_load_dwordx4 v[208:211], v190, s[22:23]
	s_add_u32 s22, s22, 0x5800
	s_addc_u32 s23, s23, 0
	global_load_dwordx4 v[212:215], v190, s[22:23]
	v_lshrrev_b32_e32 v8, 4, v2
	v_and_b32_e32 v3, 15, v2
	v_lshlrev_b32_e32 v3, 2, v3
	v_mul_u32_u24_e32 v8, 0x6000, v8
	v_add_u32_e32 v191, v8, v3
	s_lshl_b32 s19, s17, 6
	s_addk_i32 s19, 0x3000
	v_add_u32_e32 v191, s19, v191
	global_load_dword v189, v191, s[12:13]
.Lp1_nob0:
	s_lshl_b32 s8, s6, 12
	s_add_u32 s8, s40, s8
	s_addc_u32 s9, s41, 0
	global_load_dwordx4 v[68:71], v0, s[8:9]
	global_load_dwordx4 v[72:75], v0, s[8:9] offset:1024
	global_load_dwordx4 v[76:79], v0, s[8:9] offset:2048
	global_load_dwordx4 v[80:83], v0, s[8:9] offset:3072
	s_add_u32 s8, s8, 0x800000
	s_addc_u32 s9, s9, 0
	global_load_dwordx4 v[84:87], v0, s[8:9]
	global_load_dwordx4 v[88:91], v0, s[8:9] offset:1024
	global_load_dwordx4 v[92:95], v0, s[8:9] offset:2048
	global_load_dwordx4 v[96:99], v0, s[8:9] offset:3072
	s_add_u32 s8, s8, 0x800000
	s_addc_u32 s9, s9, 0
	global_load_dwordx4 v[100:103], v0, s[8:9]
	global_load_dwordx4 v[104:107], v0, s[8:9] offset:1024
	global_load_dwordx4 v[108:111], v0, s[8:9] offset:2048
	global_load_dwordx4 v[112:115], v0, s[8:9] offset:3072
	s_add_u32 s8, s8, 0x800000
	s_addc_u32 s9, s9, 0
	global_load_dwordx4 v[116:119], v0, s[8:9]
	global_load_dwordx4 v[120:123], v0, s[8:9] offset:1024
	global_load_dwordx4 v[124:127], v0, s[8:9] offset:2048
	global_load_dwordx4 v[128:131], v0, s[8:9] offset:3072
	s_add_u32 s8, s8, 0x800000
	s_addc_u32 s9, s9, 0
	s_lshl_b32 s10, s6, 11
	s_add_u32 s10, s10, 0x1e85000
	s_addc_u32 s11, 0, 0
	s_add_u32 s10, s74, s10
	s_addc_u32 s11, s75, s11
	s_cmpk_lt_u32 s16, 0xb0
	s_cbranch_scc0 .Lp1_nob1
	s_waitcnt vmcnt(16)
	v_readlane_b32 s24, v189, 0
	v_readlane_b32 s25, v189, 16
	v_readlane_b32 s26, v189, 32
	v_readlane_b32 s27, v189, 48
	v_mul_f32_e32 v216, s24, v148
	v_mul_f32_e32 v217, s24, v149
	v_mul_f32_e32 v218, s24, v150
	v_mul_f32_e32 v219, s24, v151
	v_mul_f32_e32 v220, s25, v148
	v_mul_f32_e32 v221, s25, v149
	v_mul_f32_e32 v222, s25, v150
	v_mul_f32_e32 v223, s25, v151
	v_mul_f32_e32 v224, s26, v148
	v_mul_f32_e32 v225, s26, v149
	v_mul_f32_e32 v226, s26, v150
	v_mul_f32_e32 v227, s26, v151
	v_mul_f32_e32 v228, s27, v148
	v_mul_f32_e32 v229, s27, v149
	v_mul_f32_e32 v230, s27, v150
	v_mul_f32_e32 v231, s27, v151
	v_readlane_b32 s24, v189, 1
	v_readlane_b32 s25, v189, 17
	v_readlane_b32 s26, v189, 33
	v_readlane_b32 s27, v189, 49
	v_fmac_f32_e32 v216, s24, v152
	v_fmac_f32_e32 v217, s24, v153
	v_fmac_f32_e32 v218, s24, v154
	v_fmac_f32_e32 v219, s24, v155
	v_fmac_f32_e32 v220, s25, v152
	v_fmac_f32_e32 v221, s25, v153
	v_fmac_f32_e32 v222, s25, v154
	v_fmac_f32_e32 v223, s25, v155
	v_fmac_f32_e32 v224, s26, v152
	v_fmac_f32_e32 v225, s26, v153
	v_fmac_f32_e32 v226, s26, v154
	v_fmac_f32_e32 v227, s26, v155
	v_fmac_f32_e32 v228, s27, v152
	v_fmac_f32_e32 v229, s27, v153
	v_fmac_f32_e32 v230, s27, v154
	v_fmac_f32_e32 v231, s27, v155
	v_readlane_b32 s24, v189, 2
	v_readlane_b32 s25, v189, 18
	v_readlane_b32 s26, v189, 34
	v_readlane_b32 s27, v189, 50
	v_fmac_f32_e32 v216, s24, v156
	v_fmac_f32_e32 v217, s24, v157
	v_fmac_f32_e32 v218, s24, v158
	v_fmac_f32_e32 v219, s24, v159
	v_fmac_f32_e32 v220, s25, v156
	v_fmac_f32_e32 v221, s25, v157
	v_fmac_f32_e32 v222, s25, v158
	v_fmac_f32_e32 v223, s25, v159
	v_fmac_f32_e32 v224, s26, v156
	v_fmac_f32_e32 v225, s26, v157
	v_fmac_f32_e32 v226, s26, v158
	v_fmac_f32_e32 v227, s26, v159
	v_fmac_f32_e32 v228, s27, v156
	v_fmac_f32_e32 v229, s27, v157
	v_fmac_f32_e32 v230, s27, v158
	v_fmac_f32_e32 v231, s27, v159
	v_readlane_b32 s24, v189, 3
	v_readlane_b32 s25, v189, 19
	v_readlane_b32 s26, v189, 35
	v_readlane_b32 s27, v189, 51
	v_fmac_f32_e32 v216, s24, v160
	v_fmac_f32_e32 v217, s24, v161
	v_fmac_f32_e32 v218, s24, v162
	v_fmac_f32_e32 v219, s24, v163
	v_fmac_f32_e32 v220, s25, v160
	v_fmac_f32_e32 v221, s25, v161
	v_fmac_f32_e32 v222, s25, v162
	v_fmac_f32_e32 v223, s25, v163
	v_fmac_f32_e32 v224, s26, v160
	v_fmac_f32_e32 v225, s26, v161
	v_fmac_f32_e32 v226, s26, v162
	v_fmac_f32_e32 v227, s26, v163
	v_fmac_f32_e32 v228, s27, v160
	v_fmac_f32_e32 v229, s27, v161
	v_fmac_f32_e32 v230, s27, v162
	v_fmac_f32_e32 v231, s27, v163
	v_readlane_b32 s24, v189, 4
	v_readlane_b32 s25, v189, 20
	v_readlane_b32 s26, v189, 36
	v_readlane_b32 s27, v189, 52
	v_fmac_f32_e32 v216, s24, v164
	v_fmac_f32_e32 v217, s24, v165
	v_fmac_f32_e32 v218, s24, v166
	v_fmac_f32_e32 v219, s24, v167
	v_fmac_f32_e32 v220, s25, v164
	v_fmac_f32_e32 v221, s25, v165
	v_fmac_f32_e32 v222, s25, v166
	v_fmac_f32_e32 v223, s25, v167
	v_fmac_f32_e32 v224, s26, v164
	v_fmac_f32_e32 v225, s26, v165
	v_fmac_f32_e32 v226, s26, v166
	v_fmac_f32_e32 v227, s26, v167
	v_fmac_f32_e32 v228, s27, v164
	v_fmac_f32_e32 v229, s27, v165
	v_fmac_f32_e32 v230, s27, v166
	v_fmac_f32_e32 v231, s27, v167
	v_readlane_b32 s24, v189, 5
	v_readlane_b32 s25, v189, 21
	v_readlane_b32 s26, v189, 37
	v_readlane_b32 s27, v189, 53
	v_fmac_f32_e32 v216, s24, v168
	v_fmac_f32_e32 v217, s24, v169
	v_fmac_f32_e32 v218, s24, v170
	v_fmac_f32_e32 v219, s24, v171
	v_fmac_f32_e32 v220, s25, v168
	v_fmac_f32_e32 v221, s25, v169
	v_fmac_f32_e32 v222, s25, v170
	v_fmac_f32_e32 v223, s25, v171
	v_fmac_f32_e32 v224, s26, v168
	v_fmac_f32_e32 v225, s26, v169
	v_fmac_f32_e32 v226, s26, v170
	v_fmac_f32_e32 v227, s26, v171
	v_fmac_f32_e32 v228, s27, v168
	v_fmac_f32_e32 v229, s27, v169
	v_fmac_f32_e32 v230, s27, v170
	v_fmac_f32_e32 v231, s27, v171
	v_readlane_b32 s24, v189, 6
	v_readlane_b32 s25, v189, 22
	v_readlane_b32 s26, v189, 38
	v_readlane_b32 s27, v189, 54
	v_fmac_f32_e32 v216, s24, v172
	v_fmac_f32_e32 v217, s24, v173
	v_fmac_f32_e32 v218, s24, v174
	v_fmac_f32_e32 v219, s24, v175
	v_fmac_f32_e32 v220, s25, v172
	v_fmac_f32_e32 v221, s25, v173
	v_fmac_f32_e32 v222, s25, v174
	v_fmac_f32_e32 v223, s25, v175
	v_fmac_f32_e32 v224, s26, v172
	v_fmac_f32_e32 v225, s26, v173
	v_fmac_f32_e32 v226, s26, v174
	v_fmac_f32_e32 v227, s26, v175
	v_fmac_f32_e32 v228, s27, v172
	v_fmac_f32_e32 v229, s27, v173
	v_fmac_f32_e32 v230, s27, v174
	v_fmac_f32_e32 v231, s27, v175
	v_readlane_b32 s24, v189, 7
	v_readlane_b32 s25, v189, 23
	v_readlane_b32 s26, v189, 39
	v_readlane_b32 s27, v189, 55
	v_fmac_f32_e32 v216, s24, v176
	v_fmac_f32_e32 v217, s24, v177
	v_fmac_f32_e32 v218, s24, v178
	v_fmac_f32_e32 v219, s24, v179
	v_fmac_f32_e32 v220, s25, v176
	v_fmac_f32_e32 v221, s25, v177
	v_fmac_f32_e32 v222, s25, v178
	v_fmac_f32_e32 v223, s25, v179
	v_fmac_f32_e32 v224, s26, v176
	v_fmac_f32_e32 v225, s26, v177
	v_fmac_f32_e32 v226, s26, v178
	v_fmac_f32_e32 v227, s26, v179
	v_fmac_f32_e32 v228, s27, v176
	v_fmac_f32_e32 v229, s27, v177
	v_fmac_f32_e32 v230, s27, v178
	v_fmac_f32_e32 v231, s27, v179
	v_readlane_b32 s24, v189, 8
	v_readlane_b32 s25, v189, 24
	v_readlane_b32 s26, v189, 40
	v_readlane_b32 s27, v189, 56
	v_fmac_f32_e32 v216, s24, v180
	v_fmac_f32_e32 v217, s24, v181
	v_fmac_f32_e32 v218, s24, v182
	v_fmac_f32_e32 v219, s24, v183
	v_fmac_f32_e32 v220, s25, v180
	v_fmac_f32_e32 v221, s25, v181
	v_fmac_f32_e32 v222, s25, v182
	v_fmac_f32_e32 v223, s25, v183
	v_fmac_f32_e32 v224, s26, v180
	v_fmac_f32_e32 v225, s26, v181
	v_fmac_f32_e32 v226, s26, v182
	v_fmac_f32_e32 v227, s26, v183
	v_fmac_f32_e32 v228, s27, v180
	v_fmac_f32_e32 v229, s27, v181
	v_fmac_f32_e32 v230, s27, v182
	v_fmac_f32_e32 v231, s27, v183
	v_readlane_b32 s24, v189, 9
	v_readlane_b32 s25, v189, 25
	v_readlane_b32 s26, v189, 41
	v_readlane_b32 s27, v189, 57
	v_fmac_f32_e32 v216, s24, v184
	v_fmac_f32_e32 v217, s24, v185
	v_fmac_f32_e32 v218, s24, v186
	v_fmac_f32_e32 v219, s24, v187
	v_fmac_f32_e32 v220, s25, v184
	v_fmac_f32_e32 v221, s25, v185
	v_fmac_f32_e32 v222, s25, v186
	v_fmac_f32_e32 v223, s25, v187
	v_fmac_f32_e32 v224, s26, v184
	v_fmac_f32_e32 v225, s26, v185
	v_fmac_f32_e32 v226, s26, v186
	v_fmac_f32_e32 v227, s26, v187
	v_fmac_f32_e32 v228, s27, v184
	v_fmac_f32_e32 v229, s27, v185
	v_fmac_f32_e32 v230, s27, v186
	v_fmac_f32_e32 v231, s27, v187
	v_readlane_b32 s24, v189, 10
	v_readlane_b32 s25, v189, 26
	v_readlane_b32 s26, v189, 42
	v_readlane_b32 s27, v189, 58
	v_fmac_f32_e32 v216, s24, v192
	v_fmac_f32_e32 v217, s24, v193
	v_fmac_f32_e32 v218, s24, v194
	v_fmac_f32_e32 v219, s24, v195
	v_fmac_f32_e32 v220, s25, v192
	v_fmac_f32_e32 v221, s25, v193
	v_fmac_f32_e32 v222, s25, v194
	v_fmac_f32_e32 v223, s25, v195
	v_fmac_f32_e32 v224, s26, v192
	v_fmac_f32_e32 v225, s26, v193
	v_fmac_f32_e32 v226, s26, v194
	v_fmac_f32_e32 v227, s26, v195
	v_fmac_f32_e32 v228, s27, v192
	v_fmac_f32_e32 v229, s27, v193
	v_fmac_f32_e32 v230, s27, v194
	v_fmac_f32_e32 v231, s27, v195
	v_readlane_b32 s24, v189, 11
	v_readlane_b32 s25, v189, 27
	v_readlane_b32 s26, v189, 43
	v_readlane_b32 s27, v189, 59
	v_fmac_f32_e32 v216, s24, v196
	v_fmac_f32_e32 v217, s24, v197
	v_fmac_f32_e32 v218, s24, v198
	v_fmac_f32_e32 v219, s24, v199
	v_fmac_f32_e32 v220, s25, v196
	v_fmac_f32_e32 v221, s25, v197
	v_fmac_f32_e32 v222, s25, v198
	v_fmac_f32_e32 v223, s25, v199
	v_fmac_f32_e32 v224, s26, v196
	v_fmac_f32_e32 v225, s26, v197
	v_fmac_f32_e32 v226, s26, v198
	v_fmac_f32_e32 v227, s26, v199
	v_fmac_f32_e32 v228, s27, v196
	v_fmac_f32_e32 v229, s27, v197
	v_fmac_f32_e32 v230, s27, v198
	v_fmac_f32_e32 v231, s27, v199
	v_readlane_b32 s24, v189, 12
	v_readlane_b32 s25, v189, 28
	v_readlane_b32 s26, v189, 44
	v_readlane_b32 s27, v189, 60
	v_fmac_f32_e32 v216, s24, v200
	v_fmac_f32_e32 v217, s24, v201
	v_fmac_f32_e32 v218, s24, v202
	v_fmac_f32_e32 v219, s24, v203
	v_fmac_f32_e32 v220, s25, v200
	v_fmac_f32_e32 v221, s25, v201
	v_fmac_f32_e32 v222, s25, v202
	v_fmac_f32_e32 v223, s25, v203
	v_fmac_f32_e32 v224, s26, v200
	v_fmac_f32_e32 v225, s26, v201
	v_fmac_f32_e32 v226, s26, v202
	v_fmac_f32_e32 v227, s26, v203
	v_fmac_f32_e32 v228, s27, v200
	v_fmac_f32_e32 v229, s27, v201
	v_fmac_f32_e32 v230, s27, v202
	v_fmac_f32_e32 v231, s27, v203
	v_readlane_b32 s24, v189, 13
	v_readlane_b32 s25, v189, 29
	v_readlane_b32 s26, v189, 45
	v_readlane_b32 s27, v189, 61
	v_fmac_f32_e32 v216, s24, v204
	v_fmac_f32_e32 v217, s24, v205
	v_fmac_f32_e32 v218, s24, v206
	v_fmac_f32_e32 v219, s24, v207
	v_fmac_f32_e32 v220, s25, v204
	v_fmac_f32_e32 v221, s25, v205
	v_fmac_f32_e32 v222, s25, v206
	v_fmac_f32_e32 v223, s25, v207
	v_fmac_f32_e32 v224, s26, v204
	v_fmac_f32_e32 v225, s26, v205
	v_fmac_f32_e32 v226, s26, v206
	v_fmac_f32_e32 v227, s26, v207
	v_fmac_f32_e32 v228, s27, v204
	v_fmac_f32_e32 v229, s27, v205
	v_fmac_f32_e32 v230, s27, v206
	v_fmac_f32_e32 v231, s27, v207
	v_readlane_b32 s24, v189, 14
	v_readlane_b32 s25, v189, 30
	v_readlane_b32 s26, v189, 46
	v_readlane_b32 s27, v189, 62
	v_fmac_f32_e32 v216, s24, v208
	v_fmac_f32_e32 v217, s24, v209
	v_fmac_f32_e32 v218, s24, v210
	v_fmac_f32_e32 v219, s24, v211
	v_fmac_f32_e32 v220, s25, v208
	v_fmac_f32_e32 v221, s25, v209
	v_fmac_f32_e32 v222, s25, v210
	v_fmac_f32_e32 v223, s25, v211
	v_fmac_f32_e32 v224, s26, v208
	v_fmac_f32_e32 v225, s26, v209
	v_fmac_f32_e32 v226, s26, v210
	v_fmac_f32_e32 v227, s26, v211
	v_fmac_f32_e32 v228, s27, v208
	v_fmac_f32_e32 v229, s27, v209
	v_fmac_f32_e32 v230, s27, v210
	v_fmac_f32_e32 v231, s27, v211
	v_readlane_b32 s24, v189, 15
	v_readlane_b32 s25, v189, 31
	v_readlane_b32 s26, v189, 47
	v_readlane_b32 s27, v189, 63
	v_fmac_f32_e32 v216, s24, v212
	v_fmac_f32_e32 v217, s24, v213
	v_fmac_f32_e32 v218, s24, v214
	v_fmac_f32_e32 v219, s24, v215
	v_fmac_f32_e32 v220, s25, v212
	v_fmac_f32_e32 v221, s25, v213
	v_fmac_f32_e32 v222, s25, v214
	v_fmac_f32_e32 v223, s25, v215
	v_fmac_f32_e32 v224, s26, v212
	v_fmac_f32_e32 v225, s26, v213
	v_fmac_f32_e32 v226, s26, v214
	v_fmac_f32_e32 v227, s26, v215
	v_fmac_f32_e32 v228, s27, v212
	v_fmac_f32_e32 v229, s27, v213
	v_fmac_f32_e32 v230, s27, v214
	v_fmac_f32_e32 v231, s27, v215
	s_lshl_b32 s19, s7, 12
	v_add_u32_e32 v248, s19, v0
	ds_write_b128 v248, v[216:219]
	ds_write_b128 v248, v[220:223] offset:1024
	ds_write_b128 v248, v[224:227] offset:2048
	ds_write_b128 v248, v[228:231] offset:3072
	s_waitcnt lgkmcnt(0)
	s_barrier
	s_lshl_b32 s19, s7, 9
	v_add_u32_e32 v248, s19, v1
	ds_read_b64 v[216:217], v248
	ds_read_b64 v[218:219], v248 offset:4096
	ds_read_b64 v[220:221], v248 offset:8192
	ds_read_b64 v[222:223], v248 offset:12288
	ds_read_b64 v[224:225], v248 offset:16384
	ds_read_b64 v[226:227], v248 offset:20480
	ds_read_b64 v[228:229], v248 offset:24576
	ds_read_b64 v[230:231], v248 offset:28672
	s_waitcnt lgkmcnt(0)
	v_pk_add_f32 v[216:217], v[216:217], v[218:219]
	v_pk_add_f32 v[216:217], v[216:217], v[220:221]
	v_pk_add_f32 v[216:217], v[216:217], v[222:223]
	v_pk_add_f32 v[216:217], v[216:217], v[224:225]
	v_pk_add_f32 v[216:217], v[216:217], v[226:227]
	v_pk_add_f32 v[216:217], v[216:217], v[228:229]
	v_pk_add_f32 v[216:217], v[216:217], v[230:231]
	s_and_b32 s19, s7, 1
	s_lshl_b32 s19, s19, 9
	s_lshl_b32 s24, s18, 10
	s_add_i32 s19, s19, s24
	v_add_u32_e32 v248, s19, v1
	s_lshr_b32 s24, s7, 1
	s_mul_i32 s24, s24, 0x5800
	s_add_u32 s14, s74, 0x47000
	s_addc_u32 s15, s75, 0
	s_add_u32 s14, s14, s24
	s_addc_u32 s15, s15, 0
	global_atomic_add_f32 v248, v216, s[14:15]
	global_atomic_add_f32 v248, v217, s[14:15] offset:4
